# P2 token-shift pass: element-to-(row,column) mapping changed so each wave is entirely inside or outside the tanh half (no divergent tanh)
# speedup vs baseline: 1.0176x; 1.0176x over previous
; __device__ __forceinline__ unsigned pk2(float lo, float hi) { return f2bf(lo) | (f2bf(hi) << 16); }
; __device__ __forceinline__ void phase_shift_cum(const Args& A, int gtid, int NGT, int gw, int lane) {
;     ...
;     for (int e = gtid; e < M * 64; e += NGT) {
;         const int m = e >> 6, c4 = (e & 63) * 4; const int t = m & (T - 1);
;         const f32x4 cur = *(const f32x4*)(WA + (size_t)m * 256 + c4);
;         const f32x4 prv = t ? *(const f32x4*)(WA + (size_t)(m - 1) * 256 + c4) : (f32x4){0.f, 0.f, 0.f, 0.f};
;         const f32x4 mm = *(const f32x4*)(mu + 4608 + c4);
;         f32x4 v = cur + (prv - cur) * mm;
;         if (c4 < 128) { v.x = tanhf(v.x); v.y = tanhf(v.y); v.z = tanhf(v.z); v.w = tanhf(v.w);
;             *(v2u*)(A1 + (size_t)m * LORA + c4) = (v2u){pk2(v.x, v.y), pk2(v.z, v.w)}; }
;         else *(v2u*)(A2 + (size_t)m * LORA + (c4 - 128)) = (v2u){pk2(v.x, v.y), pk2(v.z, v.w)};
;     }
.LBB0_290:
	v_lshrrev_b32_e32 v10, 6, v15
	v_bfe_u32 v91, v15, 5, 1
	v_bfe_u32 v92, v10, 2, 1
	v_and_b32_e32 v10, -5, v10
	v_lshl_or_b32 v10, v91, 2, v10
	v_ashrrev_i32_e32 v11, 31, v10
	v_and_b32_e32 v20, 31, v15
	v_lshl_or_b32 v20, v92, 5, v20
	v_lshlrev_b32_e32 v20, 2, v20
	v_lshlrev_b64 v[0:1], 10, v[10:11]
	v_lshl_add_u64 v[0:1], s[6:7], 0, v[0:1]
	v_lshlrev_b32_e32 v8, 2, v20
	v_lshl_add_u64 v[12:13], v[0:1], 0, v[8:9]
	global_load_dwordx4 v[0:3], v[12:13], off
	v_and_b32_e32 v4, 0xfff, v10
	v_cmp_ne_u32_e32 vcc, 0, v4
	v_mov_b32_e32 v4, 0
	v_mov_b32_e32 v5, 0
	v_mov_b32_e32 v6, 0
	v_mov_b32_e32 v7, 0
	s_and_saveexec_b64 s[14:15], vcc
	s_cbranch_execz .LBB0_292
	global_load_dwordx4 v[4:7], v[12:13], off offset:-1024
